# v41 plus MLA M segment cleaned of three redundant consecutive s_waitcnt and one unneeded s_nop between the QK halves (strictly equivalent instruction stream)
# speedup vs baseline: 1.0024x; 1.0024x over previous
.LBB0_1228:
	s_add_i32 s61, s51, -3
	s_add_i32 s98, s99, 0x4400
	s_cmp_eq_u32 s98, 0xcc00
	s_cselect_b32 s98, 0, s98
	v_add_u32_e32 v52, s98, v152
	ds_read_b128 v[48:51], v52 offset:32768
	ds_read_b128 v[158:161], v52 offset:32800
	ds_read_b128 v[162:165], v52 offset:41472
	ds_read_b128 v[166:169], v52 offset:41504
	ds_read_b128 v[170:173], v52 offset:32832
	ds_read_b128 v[174:177], v52 offset:32864
	ds_read_b128 v[178:181], v52 offset:41536
	ds_read_b128 v[182:185], v52 offset:41568
	ds_read_b128 v[186:189], v52 offset:32896
	ds_read_b128 v[190:193], v52 offset:32928
	ds_read_b128 v[194:197], v52 offset:41600
	ds_read_b128 v[202:205], v52 offset:41632
	s_waitcnt lgkmcnt(11)
	v_mfma_f32_32x32x16_bf16 v[64:79], v[48:51], v[80:83], v[32:47]
	s_waitcnt lgkmcnt(9)
	v_mfma_f32_32x32x16_bf16 v[48:63], v[162:165], v[80:83], v[32:47]
	v_mfma_f32_32x32x16_bf16 v[64:79], v[158:161], v[84:87], v[64:79]
	s_waitcnt lgkmcnt(8)
	v_mfma_f32_32x32x16_bf16 v[48:63], v[166:169], v[84:87], v[48:63]
	s_waitcnt lgkmcnt(7)
	v_mfma_f32_32x32x16_bf16 v[64:79], v[170:173], v[88:91], v[64:79]
	s_waitcnt lgkmcnt(5)
	v_mfma_f32_32x32x16_bf16 v[48:63], v[178:181], v[88:91], v[48:63]
	s_waitcnt lgkmcnt(0)
	s_and_b32 s62, s60, 0x6000
	v_add_u32_e32 v198, s62, v155
	ds_read_b64_tr_b16 v[158:159], v198 offset:0
	ds_read_b64_tr_b16 v[160:161], v198 offset:0x400
	ds_read_b64_tr_b16 v[162:163], v198 offset:0x800
	ds_read_b64_tr_b16 v[164:165], v198 offset:0xc00
	ds_read_b64_tr_b16 v[166:167], v198 offset:0x1000
	ds_read_b64_tr_b16 v[168:169], v198 offset:0x1400
	ds_read_b64_tr_b16 v[170:171], v198 offset:0x1800
	ds_read_b64_tr_b16 v[172:173], v198 offset:0x1c00
	ds_read_b64_tr_b16 v[178:179], v198 offset:0x200
	ds_read_b64_tr_b16 v[180:181], v198 offset:0x600
	ds_read_b64_tr_b16 v[210:211], v198 offset:0xa00
	ds_read_b64_tr_b16 v[212:213], v198 offset:0xe00
	ds_read_b64_tr_b16 v[214:215], v198 offset:0x1200
	ds_read_b64_tr_b16 v[216:217], v198 offset:0x1600
	ds_read_b64_tr_b16 v[218:219], v198 offset:0x1a00
	ds_read_b64_tr_b16 v[220:221], v198 offset:0x1e00
	v_mfma_f32_32x32x16_bf16 v[64:79], v[174:177], v[92:95], v[64:79]
	v_mfma_f32_32x32x16_bf16 v[48:63], v[182:185], v[92:95], v[48:63]
	v_mfma_f32_32x32x16_bf16 v[64:79], v[186:189], v[96:99], v[64:79]
	v_mfma_f32_32x32x16_bf16 v[48:63], v[194:197], v[96:99], v[48:63]
	v_mfma_f32_32x32x16_bf16 v[64:79], v[190:193], v[100:103], v[64:79]
	v_mfma_f32_32x32x16_bf16 v[48:63], v[202:205], v[100:103], v[48:63]
	s_waitcnt lgkmcnt(0)
	v_mfma_f32_32x32x16_bf16 v[0:15], v[140:143], v[158:161], v[0:15]
	v_mfma_f32_32x32x16_bf16 v[16:31], v[140:143], v[178:181], v[16:31]
	v_mfma_f32_32x32x16_bf16 v[0:15], v[136:139], v[162:165], v[0:15]
	v_mfma_f32_32x32x16_bf16 v[16:31], v[136:139], v[210:213], v[16:31]
	v_mfma_f32_32x32x16_bf16 v[0:15], v[132:135], v[166:169], v[0:15]
	v_mfma_f32_32x32x16_bf16 v[16:31], v[132:135], v[214:217], v[16:31]
	v_mfma_f32_32x32x16_bf16 v[0:15], v[128:131], v[170:173], v[0:15]
	v_mfma_f32_32x32x16_bf16 v[16:31], v[128:131], v[218:221], v[16:31]
	s_barrier
	s_nop 1
	v_max3_f32 v128, v64, v65, v66
	v_exp_f32_e32 v226, v64
	v_max3_f32 v129, v49, v50, v51
	v_exp_f32_e32 v227, v65
	v_max3_f32 v128, v128, v67, v68
	v_exp_f32_e32 v228, v66
	v_max3_f32 v129, v129, v52, v53
	v_exp_f32_e32 v229, v67
	v_max3_f32 v128, v128, v69, v70
	v_exp_f32_e32 v230, v68
	v_max3_f32 v129, v129, v54, v55
	v_exp_f32_e32 v231, v69
	v_max3_f32 v128, v128, v71, v72
	v_exp_f32_e32 v232, v70
	v_max3_f32 v129, v129, v56, v57
	v_exp_f32_e32 v233, v71
	v_max3_f32 v128, v128, v73, v74
	v_exp_f32_e32 v234, v72
	v_max3_f32 v129, v129, v58, v59
	v_exp_f32_e32 v235, v73
	v_max3_f32 v128, v128, v75, v76
	v_exp_f32_e32 v236, v74
	v_max3_f32 v129, v129, v60, v61
	v_exp_f32_e32 v237, v75
	v_max3_f32 v128, v128, v77, v78
	v_exp_f32_e32 v238, v76
	v_max3_f32 v129, v129, v62, v63
	v_exp_f32_e32 v239, v77
	v_max3_f32 v128, v128, v79, v48
	v_exp_f32_e32 v240, v78
	v_max_f32_e32 v128, v128, v129
	v_exp_f32_e32 v241, v79
	v_mov_b32_e32 v129, v128
	s_nop 1
	v_permlane32_swap_b32_e32 v128, v129
	v_max_f32_e32 v128, v128, v129
	v_cmp_ge_f32_e32 vcc, s83, v128
	v_mov_b32_e32 v158, 1.0
	s_cmp_eq_u64 vcc, exec
	s_cbranch_scc1 .Lsp_me
	s_branch .LBB0_1244

; #define SBAR() __builtin_amdgcn_sched_barrier(0)
; __device__ __forceinline__ float max3f(float a, float b, float c) { return __builtin_fmaxf(__builtin_fmaxf(a, b), c); }
; #define SWAIT() asm volatile("s_waitcnt vmcnt(3)" ::: "memory")
; #define VSEG(j) do { rowmax_adjust(S0, S1, m2, negm, alpha, (j) == 0); RESC(alpha); l_reg = l_reg * alpha + exp_pack(S0, S1, pa0, pa1, pa2, pa3); } while (0)
; __device__ __forceinline__ void rowmax_adjust(f32x16& p0, f32x16& p1, float& m2, f32x16& negm, float& alpha, const bool first) {
;     constexpr float THR2 = THR * 1.4426950408889634f;
;     float pmax = max3f(p0[0], p0[1], p0[2]);
; #pragma unroll
;     for (int r = 3; r < 15; r += 2) pmax = max3f(pmax, p0[r], p0[r + 1]);
;     pmax = max3f(pmax, p0[15], p1[0]);
; #pragma unroll
;     for (int r = 1; r < 15; r += 2) pmax = max3f(pmax, p1[r], p1[r + 1]);
;     pmax = fmaxf(pmax, p1[15]);
;     { auto rr = __builtin_amdgcn_permlane32_swap(__float_as_uint(pmax), __float_as_uint(pmax), false, false);
;       pmax = fmaxf(__uint_as_float(rr[0]), __uint_as_float(rr[1])); }
;     if (!first && __builtin_expect(__all(pmax <= THR2), 1)) { alpha = 1.f; }
; template <bool MLA>
; __device__ __forceinline__ void attn_core(const bf16_t* __restrict__ Qb, const bf16_t* __restrict__ Kh, const bf16_t* __restrict__ Vh, int seq, char* lds,
;                                           f32x16 (&o)[Cfg<MLA>::NCB], const int wid  , const int g  ) {
;     ...
;     __syncthreads();
;     SLOAD(SE, 0); SLOAD(SO, 64); asm volatile("s_waitcnt vmcnt(0)" ::: "memory");
;     SWRITE(0, 0, SE); SWRITE(SHM_K, SHM_V, SO);
;     SLOAD(SE, 2 * 64); SLOAD(SO, 3 * 64);
;     __syncthreads();
;     { int g_ = g; asm volatile("" : "+s"(g_)); if (g_ == 1) __syncthreads(); }
;     for (int j = 0; j < NT; j += 2) {
;         SBAR(); MSEG(j); SBAR();
;         __syncthreads();
;         SBAR(); VSEG(j);
;         SWAIT(); if (j + 2 < NT) SWRITE(((j + 2) % 3) * SHM_K, ((j + 2) & 3) * SHM_V, SE);
;         if (!(MLA && PROBE_NOLOAD)) { const int tn = (j + 4 < NT) ? j + 4 : NT - 1; SLOAD(SE, tn * 64); } SBAR();
;         __syncthreads();
;         SBAR(); MSEG(j + 1); SBAR();
;         __syncthreads();
;         SBAR(); VSEG(j + 1);
.LBB0_1236:
	s_min_u32 s10, s61, 0x7f
	s_lshl_b32 s10, s10, 6
	s_add_i32 s16, s10, 0x100
	s_add_i32 s38, s60, 0xffffa000
	s_mul_i32 s10, s16, 0x600
	s_add_u32 s10, s58, s10
	s_addc_u32 s11, s59, 0
	s_lshl_b32 s16, s16, 10
	v_lshl_add_u64 v[48:49], v[148:149], 0, s[16:17]
	global_load_dwordx4 v[112:115], v[48:49], off
	global_load_dwordx4 v[108:111], v146, s[10:11]
	global_load_dwordx4 v[104:107], v200, s[10:11]
	s_waitcnt lgkmcnt(0)
	s_barrier
	s_add_i32 s99, s98, 0x4400
	s_cmp_eq_u32 s99, 0xcc00
	s_cselect_b32 s99, 0, s99
	v_add_u32_e32 v52, s99, v152
	ds_read_b128 v[48:51], v52 offset:32768
	ds_read_b128 v[162:165], v52 offset:32800
	ds_read_b128 v[166:169], v52 offset:41472
	ds_read_b128 v[170:173], v52 offset:41504
	ds_read_b128 v[174:177], v52 offset:32832
	ds_read_b128 v[178:181], v52 offset:32864
	ds_read_b128 v[182:185], v52 offset:41536
	ds_read_b128 v[186:189], v52 offset:41568
	ds_read_b128 v[190:193], v52 offset:32896
	ds_read_b128 v[194:197], v52 offset:32928
	ds_read_b128 v[202:205], v52 offset:41600
	ds_read_b128 v[210:213], v52 offset:41632
	s_and_b32 s10, s38, 0x4000
	s_waitcnt lgkmcnt(11)
	v_mfma_f32_32x32x16_bf16 v[64:79], v[48:51], v[80:83], v[32:47]
	s_waitcnt lgkmcnt(9)
	v_mfma_f32_32x32x16_bf16 v[48:63], v[166:169], v[80:83], v[32:47]
	v_mfma_f32_32x32x16_bf16 v[64:79], v[162:165], v[84:87], v[64:79]
	s_waitcnt lgkmcnt(8)
	v_mfma_f32_32x32x16_bf16 v[48:63], v[170:173], v[84:87], v[48:63]
	s_waitcnt lgkmcnt(7)
	v_mfma_f32_32x32x16_bf16 v[64:79], v[174:177], v[88:91], v[64:79]
	s_waitcnt lgkmcnt(5)
	v_mfma_f32_32x32x16_bf16 v[48:63], v[182:185], v[88:91], v[48:63]
	v_add_u32_e32 v161, s10, v155
	s_waitcnt lgkmcnt(0)
	ds_read_b64_tr_b16 v[162:163], v161 offset:0
	ds_read_b64_tr_b16 v[164:165], v161 offset:0x400
	ds_read_b64_tr_b16 v[166:167], v161 offset:0x800
	ds_read_b64_tr_b16 v[168:169], v161 offset:0xc00
	ds_read_b64_tr_b16 v[170:171], v161 offset:0x1000
	ds_read_b64_tr_b16 v[172:173], v161 offset:0x1400
	ds_read_b64_tr_b16 v[174:175], v161 offset:0x1800
	ds_read_b64_tr_b16 v[176:177], v161 offset:0x1c00
	ds_read_b64_tr_b16 v[182:183], v161 offset:0x200
	ds_read_b64_tr_b16 v[184:185], v161 offset:0x600
	ds_read_b64_tr_b16 v[214:215], v161 offset:0xa00
	ds_read_b64_tr_b16 v[216:217], v161 offset:0xe00
	ds_read_b64_tr_b16 v[218:219], v161 offset:0x1200
	ds_read_b64_tr_b16 v[220:221], v161 offset:0x1600
	ds_read_b64_tr_b16 v[222:223], v161 offset:0x1a00
	ds_read_b64_tr_b16 v[224:225], v161 offset:0x1e00
	v_mfma_f32_32x32x16_bf16 v[64:79], v[178:181], v[92:95], v[64:79]
	v_mfma_f32_32x32x16_bf16 v[48:63], v[186:189], v[92:95], v[48:63]
	v_mfma_f32_32x32x16_bf16 v[64:79], v[190:193], v[96:99], v[64:79]
	v_mfma_f32_32x32x16_bf16 v[48:63], v[202:205], v[96:99], v[48:63]
	v_mfma_f32_32x32x16_bf16 v[64:79], v[194:197], v[100:103], v[64:79]
	v_mfma_f32_32x32x16_bf16 v[48:63], v[210:213], v[100:103], v[48:63]
	s_waitcnt lgkmcnt(0)
	v_mfma_f32_32x32x16_bf16 v[0:15], v[140:143], v[162:165], v[0:15]
	v_mfma_f32_32x32x16_bf16 v[16:31], v[140:143], v[182:185], v[16:31]
	v_mfma_f32_32x32x16_bf16 v[0:15], v[136:139], v[166:169], v[0:15]
	v_mfma_f32_32x32x16_bf16 v[16:31], v[136:139], v[214:217], v[16:31]
	v_mfma_f32_32x32x16_bf16 v[0:15], v[132:135], v[170:173], v[0:15]
	v_mfma_f32_32x32x16_bf16 v[16:31], v[132:135], v[218:221], v[16:31]
	v_mfma_f32_32x32x16_bf16 v[0:15], v[128:131], v[174:177], v[0:15]
	v_mfma_f32_32x32x16_bf16 v[16:31], v[128:131], v[222:225], v[16:31]
	s_barrier
	s_nop 1
	v_max3_f32 v128, v64, v65, v66
	v_exp_f32_e32 v226, v64
	v_max3_f32 v129, v49, v50, v51
	v_exp_f32_e32 v227, v65
	v_max3_f32 v128, v128, v67, v68
	v_exp_f32_e32 v228, v66
	v_max3_f32 v129, v129, v52, v53
	v_exp_f32_e32 v229, v67
	v_max3_f32 v128, v128, v69, v70
	v_exp_f32_e32 v230, v68
	v_max3_f32 v129, v129, v54, v55
	v_exp_f32_e32 v231, v69
	v_max3_f32 v128, v128, v71, v72
	v_exp_f32_e32 v232, v70
	v_max3_f32 v129, v129, v56, v57
	v_exp_f32_e32 v233, v71
	v_max3_f32 v128, v128, v73, v74
	v_exp_f32_e32 v234, v72
	v_max3_f32 v129, v129, v58, v59
	v_exp_f32_e32 v235, v73
	v_max3_f32 v128, v128, v75, v76
	v_exp_f32_e32 v236, v74
	v_max3_f32 v129, v129, v60, v61
	v_exp_f32_e32 v237, v75
	v_max3_f32 v128, v128, v77, v78
	v_exp_f32_e32 v238, v76
	v_max3_f32 v129, v129, v62, v63
	v_exp_f32_e32 v239, v77
	v_max3_f32 v128, v128, v79, v48
	v_exp_f32_e32 v240, v78
	v_max_f32_e32 v128, v128, v129
	v_exp_f32_e32 v241, v79
	v_mov_b32_e32 v129, v128
	s_nop 1
	v_permlane32_swap_b32_e32 v128, v129
	v_max_f32_e32 v128, v128, v129
	v_cmp_ge_f32_e32 vcc, s83, v128
	v_mov_b32_e32 v161, 1.0
	s_cmp_eq_u64 vcc, exec
	s_cbranch_scc1 .Lsp_mo
	s_branch .LBB0_1245
